# head-epilogue GEMM: removed compiler-inserted full vmcnt drain at top of every K-loop iteration (kept DMA prefetch pipeline in flight)
# speedup vs baseline: 1.0061x; 1.0061x over previous
.LBB0_216:
	s_ashr_i32 s59, s58, 31
	s_lshl_b64 s[10:11], s[58:59], 19
	s_add_u32 s50, s78, s10
	s_addc_u32 s51, s79, s11
	s_and_b64 s[10:11], s[38:39], exec
	s_cselect_b32 s12, s51, s3
	s_cselect_b32 s13, s50, s2
	s_ashr_i32 s53, s52, 31
	s_lshl_b64 s[10:11], s[52:53], 19
	s_add_u32 s60, s72, s10
	s_addc_u32 s61, s73, s11
	s_and_b64 s[10:11], s[38:39], exec
	s_cselect_b32 s14, s61, s9
	s_cselect_b32 s15, s60, s8
	s_ashr_i32 s5, s4, 31
	s_lshl_b64 s[10:11], s[4:5], 14
	s_add_u32 s2, s2, 0x40080
	s_addc_u32 s3, s3, 0
	v_lshl_add_u64 v[128:129], v[176:177], 0, s[10:11]
	s_mov_b64 s[10:11], 0x400
	s_add_u32 s5, s8, 0x100
	v_lshl_add_u64 v[130:131], v[128:129], 0, s[10:11]
	s_addc_u32 s16, s9, 0
	s_mov_b32 s17, -2
	s_mov_b64 s[8:9], 0
	s_add_u32 s18, s2, 0xfffc0080
	s_addc_u32 s19, s3, -1
	s_and_b64 s[10:11], s[8:9], exec
	s_cselect_b32 s11, s12, s19
	s_cselect_b32 s10, s13, s18
	s_add_i32 s18, 0, 0x10000
	s_and_b64 s[8:9], s[8:9], exec
	s_cselect_b32 s9, s14, s16
	s_cselect_b32 s8, s15, s5
	s_add_i32 s20, 0, 0x14000
	v_add_u32_e32 v144, s18, v217
	v_add_u32_e32 v160, s20, v217
	ds_read_b128 v[132:135], v144
	ds_read_b128 v[136:139], v144 offset:1024
	ds_read_b128 v[140:143], v144 offset:2048
	ds_read_b128 v[144:147], v144 offset:3072
	ds_read_b128 v[148:151], v160
	ds_read_b128 v[152:155], v160 offset:1024
	ds_read_b128 v[156:159], v160 offset:2048
	ds_read_b128 v[160:163], v160 offset:3072
	v_lshl_add_u64 v[168:169], s[2:3], 0, v[178:179]
	s_add_i32 m0, s7, 0xc000
	ds_read_b128 v[164:167], v218
	ds_read_b128 v[182:185], v218 offset:1024
	ds_read_b128 v[186:189], v218 offset:2048
	ds_read_b128 v[204:207], v218 offset:3072
	ds_read_b128 v[208:211], v218 offset:4096
	ds_read_b128 v[220:223], v218 offset:5120
	ds_read_b128 v[224:227], v218 offset:6144
	ds_read_b128 v[242:245], v218 offset:7168
	global_load_lds_dwordx4 v[168:169], off
	v_lshl_add_u64 v[168:169], s[2:3], 0, v[180:181]
	s_add_i32 m0, s7, 0xe000
	s_nop 0
	global_load_lds_dwordx4 v[168:169], off
	s_waitcnt vmcnt(8)
	s_waitcnt lgkmcnt(0)
	s_barrier
	s_setprio 1
	s_waitcnt lgkmcnt(0)
	v_mfma_f32_16x16x32_bf16 v[124:127], v[132:135], v[164:167], 0
	v_mfma_f32_16x16x32_bf16 v[120:123], v[140:143], v[164:167], 0
	v_mfma_f32_16x16x32_bf16 v[108:111], v[132:135], v[186:189], 0
	v_mfma_f32_16x16x32_bf16 v[104:107], v[140:143], v[186:189], 0
	v_mfma_f32_16x16x32_bf16 v[92:95], v[132:135], v[208:211], 0
	v_mfma_f32_16x16x32_bf16 v[88:91], v[140:143], v[208:211], 0
	v_mfma_f32_16x16x32_bf16 v[76:79], v[132:135], v[224:227], 0
	v_mfma_f32_16x16x32_bf16 v[72:75], v[140:143], v[224:227], 0
	v_mfma_f32_16x16x32_bf16 v[124:127], v[136:139], v[182:185], v[124:127]
	v_mfma_f32_16x16x32_bf16 v[120:123], v[144:147], v[182:185], v[120:123]
	v_mfma_f32_16x16x32_bf16 v[108:111], v[136:139], v[204:207], v[108:111]
	v_mfma_f32_16x16x32_bf16 v[104:107], v[144:147], v[204:207], v[104:107]
	v_mfma_f32_16x16x32_bf16 v[92:95], v[136:139], v[220:223], v[92:95]
	v_mfma_f32_16x16x32_bf16 v[88:91], v[144:147], v[220:223], v[88:91]
	v_mfma_f32_16x16x32_bf16 v[76:79], v[136:139], v[242:245], v[76:79]
	v_mfma_f32_16x16x32_bf16 v[72:75], v[144:147], v[242:245], v[72:75]
	s_setprio 0
	s_setprio 1
	v_mfma_f32_16x16x32_bf16 v[116:119], v[148:151], v[164:167], 0
	v_mfma_f32_16x16x32_bf16 v[112:115], v[156:159], v[164:167], 0
	v_mfma_f32_16x16x32_bf16 v[100:103], v[148:151], v[186:189], 0
	v_mfma_f32_16x16x32_bf16 v[96:99], v[156:159], v[186:189], 0
	v_mfma_f32_16x16x32_bf16 v[84:87], v[148:151], v[208:211], 0
	v_mfma_f32_16x16x32_bf16 v[80:83], v[156:159], v[208:211], 0
	v_mfma_f32_16x16x32_bf16 v[68:71], v[148:151], v[224:227], 0
	v_mfma_f32_16x16x32_bf16 v[64:67], v[156:159], v[224:227], 0
	v_mfma_f32_16x16x32_bf16 v[116:119], v[152:155], v[182:185], v[116:119]
	v_mfma_f32_16x16x32_bf16 v[112:115], v[160:163], v[182:185], v[112:115]
	v_mfma_f32_16x16x32_bf16 v[100:103], v[152:155], v[204:207], v[100:103]
	v_mfma_f32_16x16x32_bf16 v[96:99], v[160:163], v[204:207], v[96:99]
	v_mfma_f32_16x16x32_bf16 v[84:87], v[152:155], v[220:223], v[84:87]
	v_mfma_f32_16x16x32_bf16 v[80:83], v[160:163], v[220:223], v[80:83]
	v_mfma_f32_16x16x32_bf16 v[68:71], v[152:155], v[242:245], v[68:71]
	v_mfma_f32_16x16x32_bf16 v[64:67], v[160:163], v[242:245], v[64:67]
	s_setprio 0
	s_barrier
	s_add_i32 s18, s18, s29
	v_lshl_add_u64 v[168:169], s[8:9], 0, v[192:193]
	s_mov_b32 m0, s18
	ds_read_b128 v[164:167], v218 offset:16384
	ds_read_b128 v[182:185], v218 offset:17408
	ds_read_b128 v[186:189], v218 offset:18432
	ds_read_b128 v[204:207], v218 offset:19456
	ds_read_b128 v[208:211], v218 offset:20480
	ds_read_b128 v[220:223], v218 offset:21504
	ds_read_b128 v[224:227], v218 offset:22528
	ds_read_b128 v[242:245], v218 offset:23552
	global_load_lds_dwordx4 v[168:169], off
	s_add_i32 m0, s18, 0x2000
	s_add_u32 s18, s8, 0x40000
	v_lshl_add_u64 v[190:191], s[8:9], 0, v[174:175]
	s_addc_u32 s19, s9, 0
	s_add_i32 s20, s20, s29
	global_load_lds_dwordx4 v[190:191], off
	v_lshl_add_u64 v[194:195], s[18:19], 0, v[192:193]
	s_mov_b32 m0, s20
	v_lshl_add_u64 v[196:197], s[10:11], 0, v[172:173]
	global_load_lds_dwordx4 v[194:195], off
	v_lshl_add_u64 v[194:195], s[18:19], 0, v[174:175]
	s_add_i32 m0, s20, 0x2000
	s_nop 0
	global_load_lds_dwordx4 v[194:195], off
	v_lshl_add_u64 v[194:195], s[10:11], 0, v[170:171]
	s_mov_b32 m0, s7
	s_nop 0
	global_load_lds_dwordx4 v[194:195], off
	s_mov_b32 m0, s34
	s_nop 0
	global_load_lds_dwordx4 v[196:197], off
	s_waitcnt vmcnt(8)
	s_waitcnt lgkmcnt(0)
	s_barrier
	s_setprio 1
	s_waitcnt lgkmcnt(0)
	v_mfma_f32_16x16x32_bf16 v[60:63], v[132:135], v[164:167], 0
	v_mfma_f32_16x16x32_bf16 v[56:59], v[140:143], v[164:167], 0
	v_mfma_f32_16x16x32_bf16 v[44:47], v[132:135], v[186:189], 0
	v_mfma_f32_16x16x32_bf16 v[40:43], v[140:143], v[186:189], 0
	v_mfma_f32_16x16x32_bf16 v[28:31], v[132:135], v[208:211], 0
	v_mfma_f32_16x16x32_bf16 v[24:27], v[140:143], v[208:211], 0
	v_mfma_f32_16x16x32_bf16 v[12:15], v[132:135], v[224:227], 0
	v_mfma_f32_16x16x32_bf16 v[8:11], v[140:143], v[224:227], 0
	v_mfma_f32_16x16x32_bf16 v[60:63], v[136:139], v[182:185], v[60:63]
	v_mfma_f32_16x16x32_bf16 v[56:59], v[144:147], v[182:185], v[56:59]
	v_mfma_f32_16x16x32_bf16 v[44:47], v[136:139], v[204:207], v[44:47]
	v_mfma_f32_16x16x32_bf16 v[40:43], v[144:147], v[204:207], v[40:43]
	v_mfma_f32_16x16x32_bf16 v[28:31], v[136:139], v[220:223], v[28:31]
	v_mfma_f32_16x16x32_bf16 v[24:27], v[144:147], v[220:223], v[24:27]
	v_mfma_f32_16x16x32_bf16 v[12:15], v[136:139], v[242:245], v[12:15]
	v_mfma_f32_16x16x32_bf16 v[8:11], v[144:147], v[242:245], v[8:11]
	s_setprio 0
	s_setprio 1
	v_mfma_f32_16x16x32_bf16 v[52:55], v[148:151], v[164:167], 0
	v_mfma_f32_16x16x32_bf16 v[48:51], v[156:159], v[164:167], 0
	v_mfma_f32_16x16x32_bf16 v[36:39], v[148:151], v[186:189], 0
	v_mfma_f32_16x16x32_bf16 v[32:35], v[156:159], v[186:189], 0
	v_mfma_f32_16x16x32_bf16 v[20:23], v[148:151], v[208:211], 0
	v_mfma_f32_16x16x32_bf16 v[16:19], v[156:159], v[208:211], 0
	v_mfma_f32_16x16x32_bf16 v[4:7], v[148:151], v[224:227], 0
	v_mfma_f32_16x16x32_bf16 v[0:3], v[156:159], v[224:227], 0
	v_mfma_f32_16x16x32_bf16 v[52:55], v[152:155], v[182:185], v[52:55]
	v_mfma_f32_16x16x32_bf16 v[48:51], v[160:163], v[182:185], v[48:51]
	v_mfma_f32_16x16x32_bf16 v[36:39], v[152:155], v[204:207], v[36:39]
	v_mfma_f32_16x16x32_bf16 v[32:35], v[160:163], v[204:207], v[32:35]
	v_mfma_f32_16x16x32_bf16 v[20:23], v[152:155], v[220:223], v[20:23]
	v_mfma_f32_16x16x32_bf16 v[16:19], v[160:163], v[220:223], v[16:19]
	v_mfma_f32_16x16x32_bf16 v[4:7], v[152:155], v[242:245], v[4:7]
	v_mfma_f32_16x16x32_bf16 v[0:3], v[160:163], v[242:245], v[0:3]
	s_setprio 0
	s_barrier
	s_add_i32 s18, 0, 0x18000
	s_add_i32 s19, 0, 0x1c000
	v_add_u32_e32 v144, s18, v217
	v_add_u32_e32 v160, s19, v217
	ds_read_b128 v[132:135], v144
	ds_read_b128 v[136:139], v144 offset:1024
	ds_read_b128 v[140:143], v144 offset:2048
	ds_read_b128 v[144:147], v144 offset:3072
	ds_read_b128 v[148:151], v160
	ds_read_b128 v[152:155], v160 offset:1024
	ds_read_b128 v[156:159], v160 offset:2048
	ds_read_b128 v[160:163], v160 offset:3072
	s_add_u32 s10, s10, 0x40000
	s_addc_u32 s11, s11, 0
	s_mov_b32 m0, s35
	v_lshl_add_u64 v[198:199], s[10:11], 0, v[170:171]
	ds_read_b128 v[164:167], v218 offset:32768
	ds_read_b128 v[182:185], v218 offset:33792
	ds_read_b128 v[186:189], v218 offset:34816
	ds_read_b128 v[204:207], v218 offset:35840
	ds_read_b128 v[208:211], v218 offset:36864
	ds_read_b128 v[220:223], v218 offset:37888
	ds_read_b128 v[224:227], v218 offset:38912
	ds_read_b128 v[242:245], v218 offset:39936
	global_load_lds_dwordx4 v[198:199], off
	v_lshl_add_u64 v[198:199], s[10:11], 0, v[172:173]
	s_mov_b32 m0, s84
	s_nop 0
	global_load_lds_dwordx4 v[198:199], off
	s_waitcnt vmcnt(8)
	s_waitcnt lgkmcnt(0)
	s_barrier
	s_setprio 1
	s_waitcnt lgkmcnt(0)
	v_mfma_f32_16x16x32_bf16 v[124:127], v[132:135], v[164:167], v[124:127]
	v_mfma_f32_16x16x32_bf16 v[120:123], v[140:143], v[164:167], v[120:123]
	v_mfma_f32_16x16x32_bf16 v[108:111], v[132:135], v[186:189], v[108:111]
	v_mfma_f32_16x16x32_bf16 v[104:107], v[140:143], v[186:189], v[104:107]
	v_mfma_f32_16x16x32_bf16 v[92:95], v[132:135], v[208:211], v[92:95]
	v_mfma_f32_16x16x32_bf16 v[88:91], v[140:143], v[208:211], v[88:91]
	v_mfma_f32_16x16x32_bf16 v[76:79], v[132:135], v[224:227], v[76:79]
	v_mfma_f32_16x16x32_bf16 v[72:75], v[140:143], v[224:227], v[72:75]
	v_mfma_f32_16x16x32_bf16 v[124:127], v[136:139], v[182:185], v[124:127]
	v_mfma_f32_16x16x32_bf16 v[120:123], v[144:147], v[182:185], v[120:123]
	v_mfma_f32_16x16x32_bf16 v[108:111], v[136:139], v[204:207], v[108:111]
	v_mfma_f32_16x16x32_bf16 v[104:107], v[144:147], v[204:207], v[104:107]
	v_mfma_f32_16x16x32_bf16 v[92:95], v[136:139], v[220:223], v[92:95]
	v_mfma_f32_16x16x32_bf16 v[88:91], v[144:147], v[220:223], v[88:91]
	v_mfma_f32_16x16x32_bf16 v[76:79], v[136:139], v[242:245], v[76:79]
	v_mfma_f32_16x16x32_bf16 v[72:75], v[144:147], v[242:245], v[72:75]
	s_setprio 0
	s_setprio 1
	v_mfma_f32_16x16x32_bf16 v[116:119], v[148:151], v[164:167], v[116:119]
	v_mfma_f32_16x16x32_bf16 v[112:115], v[156:159], v[164:167], v[112:115]
	v_mfma_f32_16x16x32_bf16 v[100:103], v[148:151], v[186:189], v[100:103]
	v_mfma_f32_16x16x32_bf16 v[96:99], v[156:159], v[186:189], v[96:99]
	v_mfma_f32_16x16x32_bf16 v[84:87], v[148:151], v[208:211], v[84:87]
	v_mfma_f32_16x16x32_bf16 v[80:83], v[156:159], v[208:211], v[80:83]
	v_mfma_f32_16x16x32_bf16 v[68:71], v[148:151], v[224:227], v[68:71]
	v_mfma_f32_16x16x32_bf16 v[64:67], v[156:159], v[224:227], v[64:67]
	v_mfma_f32_16x16x32_bf16 v[116:119], v[152:155], v[182:185], v[116:119]
	v_mfma_f32_16x16x32_bf16 v[112:115], v[160:163], v[182:185], v[112:115]
	v_mfma_f32_16x16x32_bf16 v[100:103], v[152:155], v[204:207], v[100:103]
	v_mfma_f32_16x16x32_bf16 v[96:99], v[160:163], v[204:207], v[96:99]
	v_mfma_f32_16x16x32_bf16 v[84:87], v[152:155], v[220:223], v[84:87]
	v_mfma_f32_16x16x32_bf16 v[80:83], v[160:163], v[220:223], v[80:83]
	v_mfma_f32_16x16x32_bf16 v[68:71], v[152:155], v[242:245], v[68:71]
	v_mfma_f32_16x16x32_bf16 v[64:67], v[160:163], v[242:245], v[64:67]
	s_setprio 0
	s_barrier
	s_add_i32 s10, s18, s29
	v_lshl_add_u64 v[168:169], v[168:169], 0, s[48:49]
	s_mov_b32 m0, s10
	ds_read_b128 v[164:167], v218 offset:49152
	ds_read_b128 v[182:185], v218 offset:50176
	ds_read_b128 v[186:189], v218 offset:51200
	ds_read_b128 v[204:207], v218 offset:52224
	ds_read_b128 v[208:211], v218 offset:53248
	ds_read_b128 v[220:223], v218 offset:54272
	ds_read_b128 v[224:227], v218 offset:55296
	ds_read_b128 v[242:245], v218 offset:56320
	global_load_lds_dwordx4 v[168:169], off
	s_add_i32 m0, s10, 0x2000
	s_add_u32 s8, s8, 0x40080
	v_lshl_add_u64 v[168:169], v[190:191], 0, s[48:49]
	s_addc_u32 s9, s9, 0
	s_add_i32 s10, s19, s29
	global_load_lds_dwordx4 v[168:169], off
	v_lshl_add_u64 v[168:169], s[8:9], 0, v[192:193]
	s_mov_b32 m0, s10
	s_nop 0
	global_load_lds_dwordx4 v[168:169], off
	v_lshl_add_u64 v[168:169], s[8:9], 0, v[174:175]
	s_add_i32 m0, s10, 0x2000
	s_nop 0
	global_load_lds_dwordx4 v[168:169], off
	v_lshl_add_u64 v[168:169], v[194:195], 0, s[48:49]
	s_mov_b32 m0, s97
	s_nop 0
	global_load_lds_dwordx4 v[168:169], off
	v_lshl_add_u64 v[168:169], v[196:197], 0, s[48:49]
	s_mov_b32 m0, s26
	s_nop 0
	global_load_lds_dwordx4 v[168:169], off
	s_waitcnt vmcnt(8)
	s_waitcnt lgkmcnt(0)
	s_barrier
	s_setprio 1
	s_waitcnt lgkmcnt(0)
	v_mfma_f32_16x16x32_bf16 v[60:63], v[132:135], v[164:167], v[60:63]
	v_mfma_f32_16x16x32_bf16 v[56:59], v[140:143], v[164:167], v[56:59]
	v_mfma_f32_16x16x32_bf16 v[44:47], v[132:135], v[186:189], v[44:47]
	v_mfma_f32_16x16x32_bf16 v[40:43], v[140:143], v[186:189], v[40:43]
	v_mfma_f32_16x16x32_bf16 v[28:31], v[132:135], v[208:211], v[28:31]
	v_mfma_f32_16x16x32_bf16 v[24:27], v[140:143], v[208:211], v[24:27]
	v_mfma_f32_16x16x32_bf16 v[12:15], v[132:135], v[224:227], v[12:15]
	v_mfma_f32_16x16x32_bf16 v[8:11], v[140:143], v[224:227], v[8:11]
	v_mfma_f32_16x16x32_bf16 v[60:63], v[136:139], v[182:185], v[60:63]
	v_mfma_f32_16x16x32_bf16 v[56:59], v[144:147], v[182:185], v[56:59]
	v_mfma_f32_16x16x32_bf16 v[44:47], v[136:139], v[204:207], v[44:47]
	v_mfma_f32_16x16x32_bf16 v[40:43], v[144:147], v[204:207], v[40:43]
	v_mfma_f32_16x16x32_bf16 v[28:31], v[136:139], v[220:223], v[28:31]
	v_mfma_f32_16x16x32_bf16 v[24:27], v[144:147], v[220:223], v[24:27]
	v_mfma_f32_16x16x32_bf16 v[12:15], v[136:139], v[242:245], v[12:15]
	v_mfma_f32_16x16x32_bf16 v[8:11], v[144:147], v[242:245], v[8:11]
	s_setprio 0
	s_setprio 1
	v_mfma_f32_16x16x32_bf16 v[52:55], v[148:151], v[164:167], v[52:55]
	v_mfma_f32_16x16x32_bf16 v[48:51], v[156:159], v[164:167], v[48:51]
	v_mfma_f32_16x16x32_bf16 v[36:39], v[148:151], v[186:189], v[36:39]
	v_mfma_f32_16x16x32_bf16 v[32:35], v[156:159], v[186:189], v[32:35]
	v_mfma_f32_16x16x32_bf16 v[20:23], v[148:151], v[208:211], v[20:23]
	v_mfma_f32_16x16x32_bf16 v[16:19], v[156:159], v[208:211], v[16:19]
	v_mfma_f32_16x16x32_bf16 v[4:7], v[148:151], v[224:227], v[4:7]
	v_mfma_f32_16x16x32_bf16 v[0:3], v[156:159], v[224:227], v[0:3]
	v_mfma_f32_16x16x32_bf16 v[52:55], v[152:155], v[182:185], v[52:55]
	v_mfma_f32_16x16x32_bf16 v[48:51], v[160:163], v[182:185], v[48:51]
	v_mfma_f32_16x16x32_bf16 v[36:39], v[152:155], v[204:207], v[36:39]
	v_mfma_f32_16x16x32_bf16 v[32:35], v[160:163], v[204:207], v[32:35]
	v_mfma_f32_16x16x32_bf16 v[20:23], v[152:155], v[220:223], v[20:23]
	v_mfma_f32_16x16x32_bf16 v[16:19], v[160:163], v[220:223], v[16:19]
	v_mfma_f32_16x16x32_bf16 v[4:7], v[152:155], v[242:245], v[4:7]
	v_mfma_f32_16x16x32_bf16 v[0:3], v[160:163], v[242:245], v[0:3]
	s_setprio 0
	s_barrier
	s_add_i32 s17, s17, 2
	s_add_u32 s2, s2, 0x100
	s_addc_u32 s3, s3, 0
	s_add_u32 s5, s5, 0x100
	s_addc_u32 s16, s16, 0
	s_cmp_gt_u32 s17, 13
	s_branch .LBB0_218
.LBB0_217:
	s_add_u32 s18, s2, 0xfffc0080
	s_addc_u32 s19, s3, -1
	s_and_b64 s[10:11], s[8:9], exec
	s_cselect_b32 s11, s12, s19
	s_cselect_b32 s10, s13, s18
	s_add_i32 s18, 0, 0x10000
	s_and_b64 s[8:9], s[8:9], exec
	s_cselect_b32 s9, s14, s16
	s_cselect_b32 s8, s15, s5
	s_add_i32 s20, 0, 0x14000
	v_add_u32_e32 v144, s18, v217
	v_add_u32_e32 v160, s20, v217
	ds_read_b128 v[132:135], v144
	ds_read_b128 v[136:139], v144 offset:1024
	ds_read_b128 v[140:143], v144 offset:2048
	ds_read_b128 v[144:147], v144 offset:3072
	ds_read_b128 v[148:151], v160
	ds_read_b128 v[152:155], v160 offset:1024
	ds_read_b128 v[156:159], v160 offset:2048
	ds_read_b128 v[160:163], v160 offset:3072
	v_lshl_add_u64 v[168:169], s[2:3], 0, v[178:179]
	s_add_i32 m0, s7, 0xc000
	ds_read_b128 v[164:167], v218
	ds_read_b128 v[182:185], v218 offset:1024
	ds_read_b128 v[186:189], v218 offset:2048
	ds_read_b128 v[204:207], v218 offset:3072
	ds_read_b128 v[208:211], v218 offset:4096
	ds_read_b128 v[220:223], v218 offset:5120
	ds_read_b128 v[224:227], v218 offset:6144
	ds_read_b128 v[242:245], v218 offset:7168
	global_load_lds_dwordx4 v[168:169], off
	v_lshl_add_u64 v[168:169], s[2:3], 0, v[180:181]
	s_add_i32 m0, s7, 0xe000
	s_nop 0
	global_load_lds_dwordx4 v[168:169], off
	s_waitcnt vmcnt(8)
	s_waitcnt lgkmcnt(0)
	s_barrier
	s_setprio 1
	s_waitcnt lgkmcnt(0)
	v_mfma_f32_16x16x32_bf16 v[124:127], v[132:135], v[164:167], v[124:127]
	v_mfma_f32_16x16x32_bf16 v[120:123], v[140:143], v[164:167], v[120:123]
	v_mfma_f32_16x16x32_bf16 v[108:111], v[132:135], v[186:189], v[108:111]
	v_mfma_f32_16x16x32_bf16 v[104:107], v[140:143], v[186:189], v[104:107]
	v_mfma_f32_16x16x32_bf16 v[92:95], v[132:135], v[208:211], v[92:95]
	v_mfma_f32_16x16x32_bf16 v[88:91], v[140:143], v[208:211], v[88:91]
	v_mfma_f32_16x16x32_bf16 v[76:79], v[132:135], v[224:227], v[76:79]
	v_mfma_f32_16x16x32_bf16 v[72:75], v[140:143], v[224:227], v[72:75]
	v_mfma_f32_16x16x32_bf16 v[124:127], v[136:139], v[182:185], v[124:127]
	v_mfma_f32_16x16x32_bf16 v[120:123], v[144:147], v[182:185], v[120:123]
	v_mfma_f32_16x16x32_bf16 v[108:111], v[136:139], v[204:207], v[108:111]
	v_mfma_f32_16x16x32_bf16 v[104:107], v[144:147], v[204:207], v[104:107]
	v_mfma_f32_16x16x32_bf16 v[92:95], v[136:139], v[220:223], v[92:95]
	v_mfma_f32_16x16x32_bf16 v[88:91], v[144:147], v[220:223], v[88:91]
	v_mfma_f32_16x16x32_bf16 v[76:79], v[136:139], v[242:245], v[76:79]
	v_mfma_f32_16x16x32_bf16 v[72:75], v[144:147], v[242:245], v[72:75]
	s_setprio 0
	s_setprio 1
	v_mfma_f32_16x16x32_bf16 v[116:119], v[148:151], v[164:167], v[116:119]
	v_mfma_f32_16x16x32_bf16 v[112:115], v[156:159], v[164:167], v[112:115]
	v_mfma_f32_16x16x32_bf16 v[100:103], v[148:151], v[186:189], v[100:103]
	v_mfma_f32_16x16x32_bf16 v[96:99], v[156:159], v[186:189], v[96:99]
	v_mfma_f32_16x16x32_bf16 v[84:87], v[148:151], v[208:211], v[84:87]
	v_mfma_f32_16x16x32_bf16 v[80:83], v[156:159], v[208:211], v[80:83]
	v_mfma_f32_16x16x32_bf16 v[68:71], v[148:151], v[224:227], v[68:71]
	v_mfma_f32_16x16x32_bf16 v[64:67], v[156:159], v[224:227], v[64:67]
	v_mfma_f32_16x16x32_bf16 v[116:119], v[152:155], v[182:185], v[116:119]
	v_mfma_f32_16x16x32_bf16 v[112:115], v[160:163], v[182:185], v[112:115]
	v_mfma_f32_16x16x32_bf16 v[100:103], v[152:155], v[204:207], v[100:103]
	v_mfma_f32_16x16x32_bf16 v[96:99], v[160:163], v[204:207], v[96:99]
	v_mfma_f32_16x16x32_bf16 v[84:87], v[152:155], v[220:223], v[84:87]
	v_mfma_f32_16x16x32_bf16 v[80:83], v[160:163], v[220:223], v[80:83]
	v_mfma_f32_16x16x32_bf16 v[68:71], v[152:155], v[242:245], v[68:71]
	v_mfma_f32_16x16x32_bf16 v[64:67], v[160:163], v[242:245], v[64:67]
	s_setprio 0
	s_barrier
	s_add_i32 s18, s18, s29
	v_lshl_add_u64 v[168:169], s[8:9], 0, v[192:193]
	s_mov_b32 m0, s18
	ds_read_b128 v[164:167], v218 offset:16384
	ds_read_b128 v[182:185], v218 offset:17408
	ds_read_b128 v[186:189], v218 offset:18432
	ds_read_b128 v[204:207], v218 offset:19456
	ds_read_b128 v[208:211], v218 offset:20480
	ds_read_b128 v[220:223], v218 offset:21504
	ds_read_b128 v[224:227], v218 offset:22528
	ds_read_b128 v[242:245], v218 offset:23552
	global_load_lds_dwordx4 v[168:169], off
	s_add_i32 m0, s18, 0x2000
	s_add_u32 s18, s8, 0x40000
	v_lshl_add_u64 v[190:191], s[8:9], 0, v[174:175]
	s_addc_u32 s19, s9, 0
	s_add_i32 s20, s20, s29
	global_load_lds_dwordx4 v[190:191], off
	v_lshl_add_u64 v[194:195], s[18:19], 0, v[192:193]
	s_mov_b32 m0, s20
	v_lshl_add_u64 v[196:197], s[10:11], 0, v[172:173]
	global_load_lds_dwordx4 v[194:195], off
	v_lshl_add_u64 v[194:195], s[18:19], 0, v[174:175]
	s_add_i32 m0, s20, 0x2000
	s_nop 0
	global_load_lds_dwordx4 v[194:195], off
	v_lshl_add_u64 v[194:195], s[10:11], 0, v[170:171]
	s_mov_b32 m0, s7
	s_nop 0
	global_load_lds_dwordx4 v[194:195], off
	s_mov_b32 m0, s34
	s_nop 0
	global_load_lds_dwordx4 v[196:197], off
	s_waitcnt vmcnt(8)
	s_waitcnt lgkmcnt(0)
	s_barrier
	s_setprio 1
	s_waitcnt lgkmcnt(0)
	v_mfma_f32_16x16x32_bf16 v[60:63], v[132:135], v[164:167], v[60:63]
	v_mfma_f32_16x16x32_bf16 v[56:59], v[140:143], v[164:167], v[56:59]
	v_mfma_f32_16x16x32_bf16 v[44:47], v[132:135], v[186:189], v[44:47]
	v_mfma_f32_16x16x32_bf16 v[40:43], v[140:143], v[186:189], v[40:43]
	v_mfma_f32_16x16x32_bf16 v[28:31], v[132:135], v[208:211], v[28:31]
	v_mfma_f32_16x16x32_bf16 v[24:27], v[140:143], v[208:211], v[24:27]
	v_mfma_f32_16x16x32_bf16 v[12:15], v[132:135], v[224:227], v[12:15]
	v_mfma_f32_16x16x32_bf16 v[8:11], v[140:143], v[224:227], v[8:11]
	v_mfma_f32_16x16x32_bf16 v[60:63], v[136:139], v[182:185], v[60:63]
	v_mfma_f32_16x16x32_bf16 v[56:59], v[144:147], v[182:185], v[56:59]
	v_mfma_f32_16x16x32_bf16 v[44:47], v[136:139], v[204:207], v[44:47]
	v_mfma_f32_16x16x32_bf16 v[40:43], v[144:147], v[204:207], v[40:43]
	v_mfma_f32_16x16x32_bf16 v[28:31], v[136:139], v[220:223], v[28:31]
	v_mfma_f32_16x16x32_bf16 v[24:27], v[144:147], v[220:223], v[24:27]
	v_mfma_f32_16x16x32_bf16 v[12:15], v[136:139], v[242:245], v[12:15]
	v_mfma_f32_16x16x32_bf16 v[8:11], v[144:147], v[242:245], v[8:11]
	s_setprio 0
	s_setprio 1
	v_mfma_f32_16x16x32_bf16 v[52:55], v[148:151], v[164:167], v[52:55]
	v_mfma_f32_16x16x32_bf16 v[48:51], v[156:159], v[164:167], v[48:51]
	v_mfma_f32_16x16x32_bf16 v[36:39], v[148:151], v[186:189], v[36:39]
	v_mfma_f32_16x16x32_bf16 v[32:35], v[156:159], v[186:189], v[32:35]
	v_mfma_f32_16x16x32_bf16 v[20:23], v[148:151], v[208:211], v[20:23]
	v_mfma_f32_16x16x32_bf16 v[16:19], v[156:159], v[208:211], v[16:19]
	v_mfma_f32_16x16x32_bf16 v[4:7], v[148:151], v[224:227], v[4:7]
	v_mfma_f32_16x16x32_bf16 v[0:3], v[156:159], v[224:227], v[0:3]
	v_mfma_f32_16x16x32_bf16 v[52:55], v[152:155], v[182:185], v[52:55]
	v_mfma_f32_16x16x32_bf16 v[48:51], v[160:163], v[182:185], v[48:51]
	v_mfma_f32_16x16x32_bf16 v[36:39], v[152:155], v[204:207], v[36:39]
	v_mfma_f32_16x16x32_bf16 v[32:35], v[160:163], v[204:207], v[32:35]
	v_mfma_f32_16x16x32_bf16 v[20:23], v[152:155], v[220:223], v[20:23]
	v_mfma_f32_16x16x32_bf16 v[16:19], v[160:163], v[220:223], v[16:19]
	v_mfma_f32_16x16x32_bf16 v[4:7], v[152:155], v[242:245], v[4:7]
	v_mfma_f32_16x16x32_bf16 v[0:3], v[160:163], v[242:245], v[0:3]
	s_setprio 0
	s_barrier
	s_add_i32 s18, 0, 0x18000
	s_add_i32 s19, 0, 0x1c000
	v_add_u32_e32 v144, s18, v217
	v_add_u32_e32 v160, s19, v217
	ds_read_b128 v[132:135], v144
	ds_read_b128 v[136:139], v144 offset:1024
	ds_read_b128 v[140:143], v144 offset:2048
	ds_read_b128 v[144:147], v144 offset:3072
	ds_read_b128 v[148:151], v160
	ds_read_b128 v[152:155], v160 offset:1024
	ds_read_b128 v[156:159], v160 offset:2048
	ds_read_b128 v[160:163], v160 offset:3072
	s_add_u32 s10, s10, 0x40000
	s_addc_u32 s11, s11, 0
	s_mov_b32 m0, s35
	v_lshl_add_u64 v[198:199], s[10:11], 0, v[170:171]
	ds_read_b128 v[164:167], v218 offset:32768
	ds_read_b128 v[182:185], v218 offset:33792
	ds_read_b128 v[186:189], v218 offset:34816
	ds_read_b128 v[204:207], v218 offset:35840
	ds_read_b128 v[208:211], v218 offset:36864
	ds_read_b128 v[220:223], v218 offset:37888
	ds_read_b128 v[224:227], v218 offset:38912
	ds_read_b128 v[242:245], v218 offset:39936
	global_load_lds_dwordx4 v[198:199], off
	v_lshl_add_u64 v[198:199], s[10:11], 0, v[172:173]
	s_mov_b32 m0, s84
	s_nop 0
	global_load_lds_dwordx4 v[198:199], off
	s_waitcnt vmcnt(8)
	s_waitcnt lgkmcnt(0)
	s_barrier
	s_setprio 1
	s_waitcnt lgkmcnt(0)
	v_mfma_f32_16x16x32_bf16 v[124:127], v[132:135], v[164:167], v[124:127]
	v_mfma_f32_16x16x32_bf16 v[120:123], v[140:143], v[164:167], v[120:123]
	v_mfma_f32_16x16x32_bf16 v[108:111], v[132:135], v[186:189], v[108:111]
	v_mfma_f32_16x16x32_bf16 v[104:107], v[140:143], v[186:189], v[104:107]
	v_mfma_f32_16x16x32_bf16 v[92:95], v[132:135], v[208:211], v[92:95]
	v_mfma_f32_16x16x32_bf16 v[88:91], v[140:143], v[208:211], v[88:91]
	v_mfma_f32_16x16x32_bf16 v[76:79], v[132:135], v[224:227], v[76:79]
	v_mfma_f32_16x16x32_bf16 v[72:75], v[140:143], v[224:227], v[72:75]
	v_mfma_f32_16x16x32_bf16 v[124:127], v[136:139], v[182:185], v[124:127]
	v_mfma_f32_16x16x32_bf16 v[120:123], v[144:147], v[182:185], v[120:123]
	v_mfma_f32_16x16x32_bf16 v[108:111], v[136:139], v[204:207], v[108:111]
	v_mfma_f32_16x16x32_bf16 v[104:107], v[144:147], v[204:207], v[104:107]
	v_mfma_f32_16x16x32_bf16 v[92:95], v[136:139], v[220:223], v[92:95]
	v_mfma_f32_16x16x32_bf16 v[88:91], v[144:147], v[220:223], v[88:91]
	v_mfma_f32_16x16x32_bf16 v[76:79], v[136:139], v[242:245], v[76:79]
	v_mfma_f32_16x16x32_bf16 v[72:75], v[144:147], v[242:245], v[72:75]
	s_setprio 0
	s_setprio 1
	v_mfma_f32_16x16x32_bf16 v[116:119], v[148:151], v[164:167], v[116:119]
	v_mfma_f32_16x16x32_bf16 v[112:115], v[156:159], v[164:167], v[112:115]
	v_mfma_f32_16x16x32_bf16 v[100:103], v[148:151], v[186:189], v[100:103]
	v_mfma_f32_16x16x32_bf16 v[96:99], v[156:159], v[186:189], v[96:99]
	v_mfma_f32_16x16x32_bf16 v[84:87], v[148:151], v[208:211], v[84:87]
	v_mfma_f32_16x16x32_bf16 v[80:83], v[156:159], v[208:211], v[80:83]
	v_mfma_f32_16x16x32_bf16 v[68:71], v[148:151], v[224:227], v[68:71]
	v_mfma_f32_16x16x32_bf16 v[64:67], v[156:159], v[224:227], v[64:67]
	v_mfma_f32_16x16x32_bf16 v[116:119], v[152:155], v[182:185], v[116:119]
	v_mfma_f32_16x16x32_bf16 v[112:115], v[160:163], v[182:185], v[112:115]
	v_mfma_f32_16x16x32_bf16 v[100:103], v[152:155], v[204:207], v[100:103]
	v_mfma_f32_16x16x32_bf16 v[96:99], v[160:163], v[204:207], v[96:99]
	v_mfma_f32_16x16x32_bf16 v[84:87], v[152:155], v[220:223], v[84:87]
	v_mfma_f32_16x16x32_bf16 v[80:83], v[160:163], v[220:223], v[80:83]
	v_mfma_f32_16x16x32_bf16 v[68:71], v[152:155], v[242:245], v[68:71]
	v_mfma_f32_16x16x32_bf16 v[64:67], v[160:163], v[242:245], v[64:67]
	s_setprio 0
	s_barrier
	s_add_i32 s10, s18, s29
	v_lshl_add_u64 v[168:169], v[168:169], 0, s[48:49]
	s_mov_b32 m0, s10
	ds_read_b128 v[164:167], v218 offset:49152
	ds_read_b128 v[182:185], v218 offset:50176
	ds_read_b128 v[186:189], v218 offset:51200
	ds_read_b128 v[204:207], v218 offset:52224
	ds_read_b128 v[208:211], v218 offset:53248
	ds_read_b128 v[220:223], v218 offset:54272
	ds_read_b128 v[224:227], v218 offset:55296
	ds_read_b128 v[242:245], v218 offset:56320
	global_load_lds_dwordx4 v[168:169], off
	s_add_i32 m0, s10, 0x2000
	s_add_u32 s8, s8, 0x40080
	v_lshl_add_u64 v[168:169], v[190:191], 0, s[48:49]
	s_addc_u32 s9, s9, 0
	s_add_i32 s10, s19, s29
	global_load_lds_dwordx4 v[168:169], off
	v_lshl_add_u64 v[168:169], s[8:9], 0, v[192:193]
	s_mov_b32 m0, s10
	s_nop 0
	global_load_lds_dwordx4 v[168:169], off
	v_lshl_add_u64 v[168:169], s[8:9], 0, v[174:175]
	s_add_i32 m0, s10, 0x2000
	s_nop 0
	global_load_lds_dwordx4 v[168:169], off
	v_lshl_add_u64 v[168:169], v[194:195], 0, s[48:49]
	s_mov_b32 m0, s97
	s_nop 0
	global_load_lds_dwordx4 v[168:169], off
	v_lshl_add_u64 v[168:169], v[196:197], 0, s[48:49]
	s_mov_b32 m0, s26
	s_nop 0
	global_load_lds_dwordx4 v[168:169], off
	s_waitcnt vmcnt(8)
	s_waitcnt lgkmcnt(0)
	s_barrier
	s_setprio 1
	s_waitcnt lgkmcnt(0)
	v_mfma_f32_16x16x32_bf16 v[60:63], v[132:135], v[164:167], v[60:63]
	v_mfma_f32_16x16x32_bf16 v[56:59], v[140:143], v[164:167], v[56:59]
	v_mfma_f32_16x16x32_bf16 v[44:47], v[132:135], v[186:189], v[44:47]
	v_mfma_f32_16x16x32_bf16 v[40:43], v[140:143], v[186:189], v[40:43]
	v_mfma_f32_16x16x32_bf16 v[28:31], v[132:135], v[208:211], v[28:31]
	v_mfma_f32_16x16x32_bf16 v[24:27], v[140:143], v[208:211], v[24:27]
	v_mfma_f32_16x16x32_bf16 v[12:15], v[132:135], v[224:227], v[12:15]
	v_mfma_f32_16x16x32_bf16 v[8:11], v[140:143], v[224:227], v[8:11]
	v_mfma_f32_16x16x32_bf16 v[60:63], v[136:139], v[182:185], v[60:63]
	v_mfma_f32_16x16x32_bf16 v[56:59], v[144:147], v[182:185], v[56:59]
	v_mfma_f32_16x16x32_bf16 v[44:47], v[136:139], v[204:207], v[44:47]
	v_mfma_f32_16x16x32_bf16 v[40:43], v[144:147], v[204:207], v[40:43]
	v_mfma_f32_16x16x32_bf16 v[28:31], v[136:139], v[220:223], v[28:31]
	v_mfma_f32_16x16x32_bf16 v[24:27], v[144:147], v[220:223], v[24:27]
	v_mfma_f32_16x16x32_bf16 v[12:15], v[136:139], v[242:245], v[12:15]
	v_mfma_f32_16x16x32_bf16 v[8:11], v[144:147], v[242:245], v[8:11]
	s_setprio 0
	s_setprio 1
	v_mfma_f32_16x16x32_bf16 v[52:55], v[148:151], v[164:167], v[52:55]
	v_mfma_f32_16x16x32_bf16 v[48:51], v[156:159], v[164:167], v[48:51]
	v_mfma_f32_16x16x32_bf16 v[36:39], v[148:151], v[186:189], v[36:39]
	v_mfma_f32_16x16x32_bf16 v[32:35], v[156:159], v[186:189], v[32:35]
	v_mfma_f32_16x16x32_bf16 v[20:23], v[148:151], v[208:211], v[20:23]
	v_mfma_f32_16x16x32_bf16 v[16:19], v[156:159], v[208:211], v[16:19]
	v_mfma_f32_16x16x32_bf16 v[4:7], v[148:151], v[224:227], v[4:7]
	v_mfma_f32_16x16x32_bf16 v[0:3], v[156:159], v[224:227], v[0:3]
	v_mfma_f32_16x16x32_bf16 v[52:55], v[152:155], v[182:185], v[52:55]
	v_mfma_f32_16x16x32_bf16 v[48:51], v[160:163], v[182:185], v[48:51]
	v_mfma_f32_16x16x32_bf16 v[36:39], v[152:155], v[204:207], v[36:39]
	v_mfma_f32_16x16x32_bf16 v[32:35], v[160:163], v[204:207], v[32:35]
	v_mfma_f32_16x16x32_bf16 v[20:23], v[152:155], v[220:223], v[20:23]
	v_mfma_f32_16x16x32_bf16 v[16:19], v[160:163], v[220:223], v[16:19]
	v_mfma_f32_16x16x32_bf16 v[4:7], v[152:155], v[242:245], v[4:7]
	v_mfma_f32_16x16x32_bf16 v[0:3], v[160:163], v[242:245], v[0:3]
	s_setprio 0
	s_barrier
	s_add_i32 s17, s17, 2
	s_add_u32 s2, s2, 0x100
	s_addc_u32 s3, s3, 0
	s_add_u32 s5, s5, 0x100
	s_addc_u32 s16, s16, 0
	s_cmp_gt_u32 s17, 13
	s_cbranch_scc1 .LBB0_220
